# P2 gMLP-v half-tile epilogue rewritten by hand: packed-f32 gelu, batched cross-lane ssq reduction, cvt_pk bf16 + LDS-transposed coalesced stores
# speedup vs baseline: 1.0097x; 1.0097x over previous
.LBB0_516:
	s_andn2_b64 vcc, exec, s[2:3]
	s_cbranch_vccnz .LBB0_550
	v_lshrrev_b32_e32 v85, 4, v214
	v_and_b32_e32 v85, 3, v85
	v_and_b32_e32 v86, 15, v214
	v_lshrrev_b32_e32 v87, 6, v215
	v_lshlrev_b32_e32 v84, 13, v85
	v_lshl_add_u32 v84, v87, 10, v84
	v_lshl_add_u32 v84, v86, 1, v84
	v_xor_b32_e32 v85, 16, v214
	v_lshlrev_b32_e32 v85, 2, v85
	v_xor_b32_e32 v86, 32, v214
	v_lshlrev_b32_e32 v86, 2, v86
	v_mov_b32_e32 v88, 0x3e6d3388
	v_mov_b32_e32 v89, 0x3e6d3388
	v_mov_b32_e32 v90, 0x3f07dc22
	v_mov_b32_e32 v91, 0x3f07dc22
	v_mov_b32_e32 v92, 0xbf3a00e3
	v_mov_b32_e32 v93, 0xbf3a00e3
	v_mov_b32_e32 v94, 0x3f35f0e3
	v_mov_b32_e32 v95, 0x3f35f0e3
	v_mov_b32_e32 v96, 0xbe11a98e
	v_mov_b32_e32 v97, 0xbe11a98e
	v_mov_b32_e32 v98, 0x3e027906
	v_mov_b32_e32 v99, 0x3e027906
	v_mov_b32_e32 v100, 0xbf38aa3b
	v_mov_b32_e32 v101, 0xbf38aa3b
	s_waitcnt vmcnt(8)
	v_and_b32_e32 v64, 0x7fffffff, v60
	v_and_b32_e32 v65, 0x7fffffff, v61
	v_cmp_gt_f32_e64 s[2:3], 0, v60
	v_cmp_gt_f32_e64 s[8:9], 0, v61
	v_pk_fma_f32 v[64:65], v[64:65], v[88:89], 1.0 op_sel_hi:[1,1,0]
	v_rcp_f32_e32 v64, v64
	v_rcp_f32_e32 v65, v65
	v_pk_mul_f32 v[68:69], v[60:61], v[60:61]
	v_pk_mul_f32 v[68:69], v[68:69], v[100:101]
	v_exp_f32_e32 v68, v68
	v_exp_f32_e32 v69, v69
	v_pk_fma_f32 v[66:67], v[64:65], v[90:91], v[92:93]
	v_pk_fma_f32 v[66:67], v[64:65], v[66:67], v[94:95]
	v_pk_fma_f32 v[66:67], v[64:65], v[66:67], v[96:97]
	v_pk_fma_f32 v[66:67], v[64:65], v[66:67], v[98:99]
	v_pk_mul_f32 v[66:67], v[64:65], v[66:67]
	v_pk_mul_f32 v[66:67], v[68:69], v[66:67]
	v_pk_mul_f32 v[70:71], v[60:61], v[66:67]
	v_pk_fma_f32 v[72:73], v[60:61], v[66:67], v[60:61] neg_lo:[1,0,0] neg_hi:[1,0,0]
	v_cndmask_b32_e64 v104, v72, v70, s[2:3]
	v_cndmask_b32_e64 v105, v73, v71, s[8:9]
	v_and_b32_e32 v64, 0x7fffffff, v62
	v_and_b32_e32 v65, 0x7fffffff, v63
	v_cmp_gt_f32_e64 s[2:3], 0, v62
	v_cmp_gt_f32_e64 s[8:9], 0, v63
	v_pk_fma_f32 v[64:65], v[64:65], v[88:89], 1.0 op_sel_hi:[1,1,0]
	v_rcp_f32_e32 v64, v64
	v_rcp_f32_e32 v65, v65
	v_pk_mul_f32 v[68:69], v[62:63], v[62:63]
	v_pk_mul_f32 v[68:69], v[68:69], v[100:101]
	v_exp_f32_e32 v68, v68
	v_exp_f32_e32 v69, v69
	v_pk_fma_f32 v[66:67], v[64:65], v[90:91], v[92:93]
	v_pk_fma_f32 v[66:67], v[64:65], v[66:67], v[94:95]
	v_pk_fma_f32 v[66:67], v[64:65], v[66:67], v[96:97]
	v_pk_fma_f32 v[66:67], v[64:65], v[66:67], v[98:99]
	v_pk_mul_f32 v[66:67], v[64:65], v[66:67]
	v_pk_mul_f32 v[66:67], v[68:69], v[66:67]
	v_pk_mul_f32 v[70:71], v[62:63], v[66:67]
	v_pk_fma_f32 v[72:73], v[62:63], v[66:67], v[62:63] neg_lo:[1,0,0] neg_hi:[1,0,0]
	v_cndmask_b32_e64 v106, v72, v70, s[2:3]
	v_cndmask_b32_e64 v107, v73, v71, s[8:9]
	v_and_b32_e32 v64, 0x7fffffff, v56
	v_and_b32_e32 v65, 0x7fffffff, v57
	v_cmp_gt_f32_e64 s[2:3], 0, v56
	v_cmp_gt_f32_e64 s[8:9], 0, v57
	v_pk_fma_f32 v[64:65], v[64:65], v[88:89], 1.0 op_sel_hi:[1,1,0]
	v_rcp_f32_e32 v64, v64
	v_rcp_f32_e32 v65, v65
	v_pk_mul_f32 v[68:69], v[56:57], v[56:57]
	v_pk_mul_f32 v[68:69], v[68:69], v[100:101]
	v_exp_f32_e32 v68, v68
	v_exp_f32_e32 v69, v69
	v_pk_fma_f32 v[66:67], v[64:65], v[90:91], v[92:93]
	v_pk_fma_f32 v[66:67], v[64:65], v[66:67], v[94:95]
	v_pk_fma_f32 v[66:67], v[64:65], v[66:67], v[96:97]
	v_pk_fma_f32 v[66:67], v[64:65], v[66:67], v[98:99]
	v_pk_mul_f32 v[66:67], v[64:65], v[66:67]
	v_pk_mul_f32 v[66:67], v[68:69], v[66:67]
	v_pk_mul_f32 v[70:71], v[56:57], v[66:67]
	v_pk_fma_f32 v[72:73], v[56:57], v[66:67], v[56:57] neg_lo:[1,0,0] neg_hi:[1,0,0]
	v_cndmask_b32_e64 v108, v72, v70, s[2:3]
	v_cndmask_b32_e64 v109, v73, v71, s[8:9]
	v_and_b32_e32 v64, 0x7fffffff, v58
	v_and_b32_e32 v65, 0x7fffffff, v59
	v_cmp_gt_f32_e64 s[2:3], 0, v58
	v_cmp_gt_f32_e64 s[8:9], 0, v59
	v_pk_fma_f32 v[64:65], v[64:65], v[88:89], 1.0 op_sel_hi:[1,1,0]
	v_rcp_f32_e32 v64, v64
	v_rcp_f32_e32 v65, v65
	v_pk_mul_f32 v[68:69], v[58:59], v[58:59]
	v_pk_mul_f32 v[68:69], v[68:69], v[100:101]
	v_exp_f32_e32 v68, v68
	v_exp_f32_e32 v69, v69
	v_pk_fma_f32 v[66:67], v[64:65], v[90:91], v[92:93]
	v_pk_fma_f32 v[66:67], v[64:65], v[66:67], v[94:95]
	v_pk_fma_f32 v[66:67], v[64:65], v[66:67], v[96:97]
	v_pk_fma_f32 v[66:67], v[64:65], v[66:67], v[98:99]
	v_pk_mul_f32 v[66:67], v[64:65], v[66:67]
	v_pk_mul_f32 v[66:67], v[68:69], v[66:67]
	v_pk_mul_f32 v[70:71], v[58:59], v[66:67]
	v_pk_fma_f32 v[72:73], v[58:59], v[66:67], v[58:59] neg_lo:[1,0,0] neg_hi:[1,0,0]
	v_cndmask_b32_e64 v110, v72, v70, s[2:3]
	v_cndmask_b32_e64 v111, v73, v71, s[8:9]
	v_pk_mul_f32 v[64:65], v[104:105], v[104:105]
	v_pk_fma_f32 v[64:65], v[106:107], v[106:107], v[64:65]
	v_pk_fma_f32 v[64:65], v[108:109], v[108:109], v[64:65]
	v_pk_fma_f32 v[64:65], v[110:111], v[110:111], v[64:65]
	v_add_f32_e32 v112, v64, v65
	v_cvt_pk_bf16_f32 v120, v104, v105
	v_cvt_pk_bf16_f32 v121, v106, v107
	v_cvt_pk_bf16_f32 v122, v108, v109
	v_cvt_pk_bf16_f32 v123, v110, v111
	ds_write_b16 v84, v120 offset:0
	ds_write_b16_d16_hi v84, v120 offset:128
	ds_write_b16 v84, v121 offset:256
	ds_write_b16_d16_hi v84, v121 offset:384
	ds_write_b16 v84, v122 offset:512
	ds_write_b16_d16_hi v84, v122 offset:640
	ds_write_b16 v84, v123 offset:768
	ds_write_b16_d16_hi v84, v123 offset:896
	v_and_b32_e32 v64, 0x7fffffff, v52
	v_and_b32_e32 v65, 0x7fffffff, v53
	v_cmp_gt_f32_e64 s[2:3], 0, v52
	v_cmp_gt_f32_e64 s[8:9], 0, v53
	v_pk_fma_f32 v[64:65], v[64:65], v[88:89], 1.0 op_sel_hi:[1,1,0]
	v_rcp_f32_e32 v64, v64
	v_rcp_f32_e32 v65, v65
	v_pk_mul_f32 v[68:69], v[52:53], v[52:53]
	v_pk_mul_f32 v[68:69], v[68:69], v[100:101]
	v_exp_f32_e32 v68, v68
	v_exp_f32_e32 v69, v69
	v_pk_fma_f32 v[66:67], v[64:65], v[90:91], v[92:93]
	v_pk_fma_f32 v[66:67], v[64:65], v[66:67], v[94:95]
	v_pk_fma_f32 v[66:67], v[64:65], v[66:67], v[96:97]
	v_pk_fma_f32 v[66:67], v[64:65], v[66:67], v[98:99]
	v_pk_mul_f32 v[66:67], v[64:65], v[66:67]
	v_pk_mul_f32 v[66:67], v[68:69], v[66:67]
	v_pk_mul_f32 v[70:71], v[52:53], v[66:67]
	v_pk_fma_f32 v[72:73], v[52:53], v[66:67], v[52:53] neg_lo:[1,0,0] neg_hi:[1,0,0]
	v_cndmask_b32_e64 v104, v72, v70, s[2:3]
	v_cndmask_b32_e64 v105, v73, v71, s[8:9]
	v_and_b32_e32 v64, 0x7fffffff, v54
	v_and_b32_e32 v65, 0x7fffffff, v55
	v_cmp_gt_f32_e64 s[2:3], 0, v54
	v_cmp_gt_f32_e64 s[8:9], 0, v55
	v_pk_fma_f32 v[64:65], v[64:65], v[88:89], 1.0 op_sel_hi:[1,1,0]
	v_rcp_f32_e32 v64, v64
	v_rcp_f32_e32 v65, v65
	v_pk_mul_f32 v[68:69], v[54:55], v[54:55]
	v_pk_mul_f32 v[68:69], v[68:69], v[100:101]
	v_exp_f32_e32 v68, v68
	v_exp_f32_e32 v69, v69
	v_pk_fma_f32 v[66:67], v[64:65], v[90:91], v[92:93]
	v_pk_fma_f32 v[66:67], v[64:65], v[66:67], v[94:95]
	v_pk_fma_f32 v[66:67], v[64:65], v[66:67], v[96:97]
	v_pk_fma_f32 v[66:67], v[64:65], v[66:67], v[98:99]
	v_pk_mul_f32 v[66:67], v[64:65], v[66:67]
	v_pk_mul_f32 v[66:67], v[68:69], v[66:67]
	v_pk_mul_f32 v[70:71], v[54:55], v[66:67]
	v_pk_fma_f32 v[72:73], v[54:55], v[66:67], v[54:55] neg_lo:[1,0,0] neg_hi:[1,0,0]
	v_cndmask_b32_e64 v106, v72, v70, s[2:3]
	v_cndmask_b32_e64 v107, v73, v71, s[8:9]
	v_and_b32_e32 v64, 0x7fffffff, v48
	v_and_b32_e32 v65, 0x7fffffff, v49
	v_cmp_gt_f32_e64 s[2:3], 0, v48
	v_cmp_gt_f32_e64 s[8:9], 0, v49
	v_pk_fma_f32 v[64:65], v[64:65], v[88:89], 1.0 op_sel_hi:[1,1,0]
	v_rcp_f32_e32 v64, v64
	v_rcp_f32_e32 v65, v65
	v_pk_mul_f32 v[68:69], v[48:49], v[48:49]
	v_pk_mul_f32 v[68:69], v[68:69], v[100:101]
	v_exp_f32_e32 v68, v68
	v_exp_f32_e32 v69, v69
	v_pk_fma_f32 v[66:67], v[64:65], v[90:91], v[92:93]
	v_pk_fma_f32 v[66:67], v[64:65], v[66:67], v[94:95]
	v_pk_fma_f32 v[66:67], v[64:65], v[66:67], v[96:97]
	v_pk_fma_f32 v[66:67], v[64:65], v[66:67], v[98:99]
	v_pk_mul_f32 v[66:67], v[64:65], v[66:67]
	v_pk_mul_f32 v[66:67], v[68:69], v[66:67]
	v_pk_mul_f32 v[70:71], v[48:49], v[66:67]
	v_pk_fma_f32 v[72:73], v[48:49], v[66:67], v[48:49] neg_lo:[1,0,0] neg_hi:[1,0,0]
	v_cndmask_b32_e64 v108, v72, v70, s[2:3]
	v_cndmask_b32_e64 v109, v73, v71, s[8:9]
	v_and_b32_e32 v64, 0x7fffffff, v50
	v_and_b32_e32 v65, 0x7fffffff, v51
	v_cmp_gt_f32_e64 s[2:3], 0, v50
	v_cmp_gt_f32_e64 s[8:9], 0, v51
	v_pk_fma_f32 v[64:65], v[64:65], v[88:89], 1.0 op_sel_hi:[1,1,0]
	v_rcp_f32_e32 v64, v64
	v_rcp_f32_e32 v65, v65
	v_pk_mul_f32 v[68:69], v[50:51], v[50:51]
	v_pk_mul_f32 v[68:69], v[68:69], v[100:101]
	v_exp_f32_e32 v68, v68
	v_exp_f32_e32 v69, v69
	v_pk_fma_f32 v[66:67], v[64:65], v[90:91], v[92:93]
	v_pk_fma_f32 v[66:67], v[64:65], v[66:67], v[94:95]
	v_pk_fma_f32 v[66:67], v[64:65], v[66:67], v[96:97]
	v_pk_fma_f32 v[66:67], v[64:65], v[66:67], v[98:99]
	v_pk_mul_f32 v[66:67], v[64:65], v[66:67]
	v_pk_mul_f32 v[66:67], v[68:69], v[66:67]
	v_pk_mul_f32 v[70:71], v[50:51], v[66:67]
	v_pk_fma_f32 v[72:73], v[50:51], v[66:67], v[50:51] neg_lo:[1,0,0] neg_hi:[1,0,0]
	v_cndmask_b32_e64 v110, v72, v70, s[2:3]
	v_cndmask_b32_e64 v111, v73, v71, s[8:9]
	v_pk_mul_f32 v[64:65], v[104:105], v[104:105]
	v_pk_fma_f32 v[64:65], v[106:107], v[106:107], v[64:65]
	v_pk_fma_f32 v[64:65], v[108:109], v[108:109], v[64:65]
	v_pk_fma_f32 v[64:65], v[110:111], v[110:111], v[64:65]
	v_add_f32_e32 v113, v64, v65
	v_cvt_pk_bf16_f32 v120, v104, v105
	v_cvt_pk_bf16_f32 v121, v106, v107
	v_cvt_pk_bf16_f32 v122, v108, v109
	v_cvt_pk_bf16_f32 v123, v110, v111
	ds_write_b16 v84, v120 offset:32
	ds_write_b16_d16_hi v84, v120 offset:160
	ds_write_b16 v84, v121 offset:288
	ds_write_b16_d16_hi v84, v121 offset:416
	ds_write_b16 v84, v122 offset:544
	ds_write_b16_d16_hi v84, v122 offset:672
	ds_write_b16 v84, v123 offset:800
	ds_write_b16_d16_hi v84, v123 offset:928
	v_and_b32_e32 v64, 0x7fffffff, v44
	v_and_b32_e32 v65, 0x7fffffff, v45
	v_cmp_gt_f32_e64 s[2:3], 0, v44
	v_cmp_gt_f32_e64 s[8:9], 0, v45
	v_pk_fma_f32 v[64:65], v[64:65], v[88:89], 1.0 op_sel_hi:[1,1,0]
	v_rcp_f32_e32 v64, v64
	v_rcp_f32_e32 v65, v65
	v_pk_mul_f32 v[68:69], v[44:45], v[44:45]
	v_pk_mul_f32 v[68:69], v[68:69], v[100:101]
	v_exp_f32_e32 v68, v68
	v_exp_f32_e32 v69, v69
	v_pk_fma_f32 v[66:67], v[64:65], v[90:91], v[92:93]
	v_pk_fma_f32 v[66:67], v[64:65], v[66:67], v[94:95]
	v_pk_fma_f32 v[66:67], v[64:65], v[66:67], v[96:97]
	v_pk_fma_f32 v[66:67], v[64:65], v[66:67], v[98:99]
	v_pk_mul_f32 v[66:67], v[64:65], v[66:67]
	v_pk_mul_f32 v[66:67], v[68:69], v[66:67]
	v_pk_mul_f32 v[70:71], v[44:45], v[66:67]
	v_pk_fma_f32 v[72:73], v[44:45], v[66:67], v[44:45] neg_lo:[1,0,0] neg_hi:[1,0,0]
	v_cndmask_b32_e64 v104, v72, v70, s[2:3]
	v_cndmask_b32_e64 v105, v73, v71, s[8:9]
	v_and_b32_e32 v64, 0x7fffffff, v46
	v_and_b32_e32 v65, 0x7fffffff, v47
	v_cmp_gt_f32_e64 s[2:3], 0, v46
	v_cmp_gt_f32_e64 s[8:9], 0, v47
	v_pk_fma_f32 v[64:65], v[64:65], v[88:89], 1.0 op_sel_hi:[1,1,0]
	v_rcp_f32_e32 v64, v64
	v_rcp_f32_e32 v65, v65
	v_pk_mul_f32 v[68:69], v[46:47], v[46:47]
	v_pk_mul_f32 v[68:69], v[68:69], v[100:101]
	v_exp_f32_e32 v68, v68
	v_exp_f32_e32 v69, v69
	v_pk_fma_f32 v[66:67], v[64:65], v[90:91], v[92:93]
	v_pk_fma_f32 v[66:67], v[64:65], v[66:67], v[94:95]
	v_pk_fma_f32 v[66:67], v[64:65], v[66:67], v[96:97]
	v_pk_fma_f32 v[66:67], v[64:65], v[66:67], v[98:99]
	v_pk_mul_f32 v[66:67], v[64:65], v[66:67]
	v_pk_mul_f32 v[66:67], v[68:69], v[66:67]
	v_pk_mul_f32 v[70:71], v[46:47], v[66:67]
	v_pk_fma_f32 v[72:73], v[46:47], v[66:67], v[46:47] neg_lo:[1,0,0] neg_hi:[1,0,0]
	v_cndmask_b32_e64 v106, v72, v70, s[2:3]
	v_cndmask_b32_e64 v107, v73, v71, s[8:9]
	v_and_b32_e32 v64, 0x7fffffff, v40
	v_and_b32_e32 v65, 0x7fffffff, v41
	v_cmp_gt_f32_e64 s[2:3], 0, v40
	v_cmp_gt_f32_e64 s[8:9], 0, v41
	v_pk_fma_f32 v[64:65], v[64:65], v[88:89], 1.0 op_sel_hi:[1,1,0]
	v_rcp_f32_e32 v64, v64
	v_rcp_f32_e32 v65, v65
	v_pk_mul_f32 v[68:69], v[40:41], v[40:41]
	v_pk_mul_f32 v[68:69], v[68:69], v[100:101]
	v_exp_f32_e32 v68, v68
	v_exp_f32_e32 v69, v69
	v_pk_fma_f32 v[66:67], v[64:65], v[90:91], v[92:93]
	v_pk_fma_f32 v[66:67], v[64:65], v[66:67], v[94:95]
	v_pk_fma_f32 v[66:67], v[64:65], v[66:67], v[96:97]
	v_pk_fma_f32 v[66:67], v[64:65], v[66:67], v[98:99]
	v_pk_mul_f32 v[66:67], v[64:65], v[66:67]
	v_pk_mul_f32 v[66:67], v[68:69], v[66:67]
	v_pk_mul_f32 v[70:71], v[40:41], v[66:67]
	v_pk_fma_f32 v[72:73], v[40:41], v[66:67], v[40:41] neg_lo:[1,0,0] neg_hi:[1,0,0]
	v_cndmask_b32_e64 v108, v72, v70, s[2:3]
	v_cndmask_b32_e64 v109, v73, v71, s[8:9]
	v_and_b32_e32 v64, 0x7fffffff, v42
	v_and_b32_e32 v65, 0x7fffffff, v43
	v_cmp_gt_f32_e64 s[2:3], 0, v42
	v_cmp_gt_f32_e64 s[8:9], 0, v43
	v_pk_fma_f32 v[64:65], v[64:65], v[88:89], 1.0 op_sel_hi:[1,1,0]
	v_rcp_f32_e32 v64, v64
	v_rcp_f32_e32 v65, v65
	v_pk_mul_f32 v[68:69], v[42:43], v[42:43]
	v_pk_mul_f32 v[68:69], v[68:69], v[100:101]
	v_exp_f32_e32 v68, v68
	v_exp_f32_e32 v69, v69
	v_pk_fma_f32 v[66:67], v[64:65], v[90:91], v[92:93]
	v_pk_fma_f32 v[66:67], v[64:65], v[66:67], v[94:95]
	v_pk_fma_f32 v[66:67], v[64:65], v[66:67], v[96:97]
	v_pk_fma_f32 v[66:67], v[64:65], v[66:67], v[98:99]
	v_pk_mul_f32 v[66:67], v[64:65], v[66:67]
	v_pk_mul_f32 v[66:67], v[68:69], v[66:67]
	v_pk_mul_f32 v[70:71], v[42:43], v[66:67]
	v_pk_fma_f32 v[72:73], v[42:43], v[66:67], v[42:43] neg_lo:[1,0,0] neg_hi:[1,0,0]
	v_cndmask_b32_e64 v110, v72, v70, s[2:3]
	v_cndmask_b32_e64 v111, v73, v71, s[8:9]
	v_pk_mul_f32 v[64:65], v[104:105], v[104:105]
	v_pk_fma_f32 v[64:65], v[106:107], v[106:107], v[64:65]
	v_pk_fma_f32 v[64:65], v[108:109], v[108:109], v[64:65]
	v_pk_fma_f32 v[64:65], v[110:111], v[110:111], v[64:65]
	v_add_f32_e32 v114, v64, v65
	v_cvt_pk_bf16_f32 v120, v104, v105
	v_cvt_pk_bf16_f32 v121, v106, v107
	v_cvt_pk_bf16_f32 v122, v108, v109
	v_cvt_pk_bf16_f32 v123, v110, v111
	ds_write_b16 v84, v120 offset:64
	ds_write_b16_d16_hi v84, v120 offset:192
	ds_write_b16 v84, v121 offset:320
	ds_write_b16_d16_hi v84, v121 offset:448
	ds_write_b16 v84, v122 offset:576
	ds_write_b16_d16_hi v84, v122 offset:704
	ds_write_b16 v84, v123 offset:832
	ds_write_b16_d16_hi v84, v123 offset:960
	v_and_b32_e32 v64, 0x7fffffff, v36
	v_and_b32_e32 v65, 0x7fffffff, v37
	v_cmp_gt_f32_e64 s[2:3], 0, v36
	v_cmp_gt_f32_e64 s[8:9], 0, v37
	v_pk_fma_f32 v[64:65], v[64:65], v[88:89], 1.0 op_sel_hi:[1,1,0]
	v_rcp_f32_e32 v64, v64
	v_rcp_f32_e32 v65, v65
	v_pk_mul_f32 v[68:69], v[36:37], v[36:37]
	v_pk_mul_f32 v[68:69], v[68:69], v[100:101]
	v_exp_f32_e32 v68, v68
	v_exp_f32_e32 v69, v69
	v_pk_fma_f32 v[66:67], v[64:65], v[90:91], v[92:93]
	v_pk_fma_f32 v[66:67], v[64:65], v[66:67], v[94:95]
	v_pk_fma_f32 v[66:67], v[64:65], v[66:67], v[96:97]
	v_pk_fma_f32 v[66:67], v[64:65], v[66:67], v[98:99]
	v_pk_mul_f32 v[66:67], v[64:65], v[66:67]
	v_pk_mul_f32 v[66:67], v[68:69], v[66:67]
	v_pk_mul_f32 v[70:71], v[36:37], v[66:67]
	v_pk_fma_f32 v[72:73], v[36:37], v[66:67], v[36:37] neg_lo:[1,0,0] neg_hi:[1,0,0]
	v_cndmask_b32_e64 v104, v72, v70, s[2:3]
	v_cndmask_b32_e64 v105, v73, v71, s[8:9]
	v_and_b32_e32 v64, 0x7fffffff, v38
	v_and_b32_e32 v65, 0x7fffffff, v39
	v_cmp_gt_f32_e64 s[2:3], 0, v38
	v_cmp_gt_f32_e64 s[8:9], 0, v39
	v_pk_fma_f32 v[64:65], v[64:65], v[88:89], 1.0 op_sel_hi:[1,1,0]
	v_rcp_f32_e32 v64, v64
	v_rcp_f32_e32 v65, v65
	v_pk_mul_f32 v[68:69], v[38:39], v[38:39]
	v_pk_mul_f32 v[68:69], v[68:69], v[100:101]
	v_exp_f32_e32 v68, v68
	v_exp_f32_e32 v69, v69
	v_pk_fma_f32 v[66:67], v[64:65], v[90:91], v[92:93]
	v_pk_fma_f32 v[66:67], v[64:65], v[66:67], v[94:95]
	v_pk_fma_f32 v[66:67], v[64:65], v[66:67], v[96:97]
	v_pk_fma_f32 v[66:67], v[64:65], v[66:67], v[98:99]
	v_pk_mul_f32 v[66:67], v[64:65], v[66:67]
	v_pk_mul_f32 v[66:67], v[68:69], v[66:67]
	v_pk_mul_f32 v[70:71], v[38:39], v[66:67]
	v_pk_fma_f32 v[72:73], v[38:39], v[66:67], v[38:39] neg_lo:[1,0,0] neg_hi:[1,0,0]
	v_cndmask_b32_e64 v106, v72, v70, s[2:3]
	v_cndmask_b32_e64 v107, v73, v71, s[8:9]
	v_and_b32_e32 v64, 0x7fffffff, v32
	v_and_b32_e32 v65, 0x7fffffff, v33
	v_cmp_gt_f32_e64 s[2:3], 0, v32
	v_cmp_gt_f32_e64 s[8:9], 0, v33
	v_pk_fma_f32 v[64:65], v[64:65], v[88:89], 1.0 op_sel_hi:[1,1,0]
	v_rcp_f32_e32 v64, v64
	v_rcp_f32_e32 v65, v65
	v_pk_mul_f32 v[68:69], v[32:33], v[32:33]
	v_pk_mul_f32 v[68:69], v[68:69], v[100:101]
	v_exp_f32_e32 v68, v68
	v_exp_f32_e32 v69, v69
	v_pk_fma_f32 v[66:67], v[64:65], v[90:91], v[92:93]
	v_pk_fma_f32 v[66:67], v[64:65], v[66:67], v[94:95]
	v_pk_fma_f32 v[66:67], v[64:65], v[66:67], v[96:97]
	v_pk_fma_f32 v[66:67], v[64:65], v[66:67], v[98:99]
	v_pk_mul_f32 v[66:67], v[64:65], v[66:67]
	v_pk_mul_f32 v[66:67], v[68:69], v[66:67]
	v_pk_mul_f32 v[70:71], v[32:33], v[66:67]
	v_pk_fma_f32 v[72:73], v[32:33], v[66:67], v[32:33] neg_lo:[1,0,0] neg_hi:[1,0,0]
	v_cndmask_b32_e64 v108, v72, v70, s[2:3]
	v_cndmask_b32_e64 v109, v73, v71, s[8:9]
	v_and_b32_e32 v64, 0x7fffffff, v34
	v_and_b32_e32 v65, 0x7fffffff, v35
	v_cmp_gt_f32_e64 s[2:3], 0, v34
	v_cmp_gt_f32_e64 s[8:9], 0, v35
	v_pk_fma_f32 v[64:65], v[64:65], v[88:89], 1.0 op_sel_hi:[1,1,0]
	v_rcp_f32_e32 v64, v64
	v_rcp_f32_e32 v65, v65
	v_pk_mul_f32 v[68:69], v[34:35], v[34:35]
	v_pk_mul_f32 v[68:69], v[68:69], v[100:101]
	v_exp_f32_e32 v68, v68
	v_exp_f32_e32 v69, v69
	v_pk_fma_f32 v[66:67], v[64:65], v[90:91], v[92:93]
	v_pk_fma_f32 v[66:67], v[64:65], v[66:67], v[94:95]
	v_pk_fma_f32 v[66:67], v[64:65], v[66:67], v[96:97]
	v_pk_fma_f32 v[66:67], v[64:65], v[66:67], v[98:99]
	v_pk_mul_f32 v[66:67], v[64:65], v[66:67]
	v_pk_mul_f32 v[66:67], v[68:69], v[66:67]
	v_pk_mul_f32 v[70:71], v[34:35], v[66:67]
	v_pk_fma_f32 v[72:73], v[34:35], v[66:67], v[34:35] neg_lo:[1,0,0] neg_hi:[1,0,0]
	v_cndmask_b32_e64 v110, v72, v70, s[2:3]
	v_cndmask_b32_e64 v111, v73, v71, s[8:9]
	v_pk_mul_f32 v[64:65], v[104:105], v[104:105]
	v_pk_fma_f32 v[64:65], v[106:107], v[106:107], v[64:65]
	v_pk_fma_f32 v[64:65], v[108:109], v[108:109], v[64:65]
	v_pk_fma_f32 v[64:65], v[110:111], v[110:111], v[64:65]
	v_add_f32_e32 v115, v64, v65
	v_cvt_pk_bf16_f32 v120, v104, v105
	v_cvt_pk_bf16_f32 v121, v106, v107
	v_cvt_pk_bf16_f32 v122, v108, v109
	v_cvt_pk_bf16_f32 v123, v110, v111
	ds_write_b16 v84, v120 offset:96
	ds_write_b16_d16_hi v84, v120 offset:224
	ds_write_b16 v84, v121 offset:352
	ds_write_b16_d16_hi v84, v121 offset:480
	ds_write_b16 v84, v122 offset:608
	ds_write_b16_d16_hi v84, v122 offset:736
	ds_write_b16 v84, v123 offset:864
	ds_write_b16_d16_hi v84, v123 offset:992
	v_and_b32_e32 v64, 0x7fffffff, v28
	v_and_b32_e32 v65, 0x7fffffff, v29
	v_cmp_gt_f32_e64 s[2:3], 0, v28
	v_cmp_gt_f32_e64 s[8:9], 0, v29
	v_pk_fma_f32 v[64:65], v[64:65], v[88:89], 1.0 op_sel_hi:[1,1,0]
	v_rcp_f32_e32 v64, v64
	v_rcp_f32_e32 v65, v65
	v_pk_mul_f32 v[68:69], v[28:29], v[28:29]
	v_pk_mul_f32 v[68:69], v[68:69], v[100:101]
	v_exp_f32_e32 v68, v68
	v_exp_f32_e32 v69, v69
	v_pk_fma_f32 v[66:67], v[64:65], v[90:91], v[92:93]
	v_pk_fma_f32 v[66:67], v[64:65], v[66:67], v[94:95]
	v_pk_fma_f32 v[66:67], v[64:65], v[66:67], v[96:97]
	v_pk_fma_f32 v[66:67], v[64:65], v[66:67], v[98:99]
	v_pk_mul_f32 v[66:67], v[64:65], v[66:67]
	v_pk_mul_f32 v[66:67], v[68:69], v[66:67]
	v_pk_mul_f32 v[70:71], v[28:29], v[66:67]
	v_pk_fma_f32 v[72:73], v[28:29], v[66:67], v[28:29] neg_lo:[1,0,0] neg_hi:[1,0,0]
	v_cndmask_b32_e64 v104, v72, v70, s[2:3]
	v_cndmask_b32_e64 v105, v73, v71, s[8:9]
	v_and_b32_e32 v64, 0x7fffffff, v30
	v_and_b32_e32 v65, 0x7fffffff, v31
	v_cmp_gt_f32_e64 s[2:3], 0, v30
	v_cmp_gt_f32_e64 s[8:9], 0, v31
	v_pk_fma_f32 v[64:65], v[64:65], v[88:89], 1.0 op_sel_hi:[1,1,0]
	v_rcp_f32_e32 v64, v64
	v_rcp_f32_e32 v65, v65
	v_pk_mul_f32 v[68:69], v[30:31], v[30:31]
	v_pk_mul_f32 v[68:69], v[68:69], v[100:101]
	v_exp_f32_e32 v68, v68
	v_exp_f32_e32 v69, v69
	v_pk_fma_f32 v[66:67], v[64:65], v[90:91], v[92:93]
	v_pk_fma_f32 v[66:67], v[64:65], v[66:67], v[94:95]
	v_pk_fma_f32 v[66:67], v[64:65], v[66:67], v[96:97]
	v_pk_fma_f32 v[66:67], v[64:65], v[66:67], v[98:99]
	v_pk_mul_f32 v[66:67], v[64:65], v[66:67]
	v_pk_mul_f32 v[66:67], v[68:69], v[66:67]
	v_pk_mul_f32 v[70:71], v[30:31], v[66:67]
	v_pk_fma_f32 v[72:73], v[30:31], v[66:67], v[30:31] neg_lo:[1,0,0] neg_hi:[1,0,0]
	v_cndmask_b32_e64 v106, v72, v70, s[2:3]
	v_cndmask_b32_e64 v107, v73, v71, s[8:9]
	v_and_b32_e32 v64, 0x7fffffff, v24
	v_and_b32_e32 v65, 0x7fffffff, v25
	v_cmp_gt_f32_e64 s[2:3], 0, v24
	v_cmp_gt_f32_e64 s[8:9], 0, v25
	v_pk_fma_f32 v[64:65], v[64:65], v[88:89], 1.0 op_sel_hi:[1,1,0]
	v_rcp_f32_e32 v64, v64
	v_rcp_f32_e32 v65, v65
	v_pk_mul_f32 v[68:69], v[24:25], v[24:25]
	v_pk_mul_f32 v[68:69], v[68:69], v[100:101]
	v_exp_f32_e32 v68, v68
	v_exp_f32_e32 v69, v69
	v_pk_fma_f32 v[66:67], v[64:65], v[90:91], v[92:93]
	v_pk_fma_f32 v[66:67], v[64:65], v[66:67], v[94:95]
	v_pk_fma_f32 v[66:67], v[64:65], v[66:67], v[96:97]
	v_pk_fma_f32 v[66:67], v[64:65], v[66:67], v[98:99]
	v_pk_mul_f32 v[66:67], v[64:65], v[66:67]
	v_pk_mul_f32 v[66:67], v[68:69], v[66:67]
	v_pk_mul_f32 v[70:71], v[24:25], v[66:67]
	v_pk_fma_f32 v[72:73], v[24:25], v[66:67], v[24:25] neg_lo:[1,0,0] neg_hi:[1,0,0]
	v_cndmask_b32_e64 v108, v72, v70, s[2:3]
	v_cndmask_b32_e64 v109, v73, v71, s[8:9]
	v_and_b32_e32 v64, 0x7fffffff, v26
	v_and_b32_e32 v65, 0x7fffffff, v27
	v_cmp_gt_f32_e64 s[2:3], 0, v26
	v_cmp_gt_f32_e64 s[8:9], 0, v27
	v_pk_fma_f32 v[64:65], v[64:65], v[88:89], 1.0 op_sel_hi:[1,1,0]
	v_rcp_f32_e32 v64, v64
	v_rcp_f32_e32 v65, v65
	v_pk_mul_f32 v[68:69], v[26:27], v[26:27]
	v_pk_mul_f32 v[68:69], v[68:69], v[100:101]
	v_exp_f32_e32 v68, v68
	v_exp_f32_e32 v69, v69
	v_pk_fma_f32 v[66:67], v[64:65], v[90:91], v[92:93]
	v_pk_fma_f32 v[66:67], v[64:65], v[66:67], v[94:95]
	v_pk_fma_f32 v[66:67], v[64:65], v[66:67], v[96:97]
	v_pk_fma_f32 v[66:67], v[64:65], v[66:67], v[98:99]
	v_pk_mul_f32 v[66:67], v[64:65], v[66:67]
	v_pk_mul_f32 v[66:67], v[68:69], v[66:67]
	v_pk_mul_f32 v[70:71], v[26:27], v[66:67]
	v_pk_fma_f32 v[72:73], v[26:27], v[66:67], v[26:27] neg_lo:[1,0,0] neg_hi:[1,0,0]
	v_cndmask_b32_e64 v110, v72, v70, s[2:3]
	v_cndmask_b32_e64 v111, v73, v71, s[8:9]
	v_pk_mul_f32 v[64:65], v[104:105], v[104:105]
	v_pk_fma_f32 v[64:65], v[106:107], v[106:107], v[64:65]
	v_pk_fma_f32 v[64:65], v[108:109], v[108:109], v[64:65]
	v_pk_fma_f32 v[64:65], v[110:111], v[110:111], v[64:65]
	v_add_f32_e32 v116, v64, v65
	v_cvt_pk_bf16_f32 v120, v104, v105
	v_cvt_pk_bf16_f32 v121, v106, v107
	v_cvt_pk_bf16_f32 v122, v108, v109
	v_cvt_pk_bf16_f32 v123, v110, v111
	ds_write_b16 v84, v120 offset:32768
	ds_write_b16_d16_hi v84, v120 offset:32896
	ds_write_b16 v84, v121 offset:33024
	ds_write_b16_d16_hi v84, v121 offset:33152
	ds_write_b16 v84, v122 offset:33280
	ds_write_b16_d16_hi v84, v122 offset:33408
	ds_write_b16 v84, v123 offset:33536
	ds_write_b16_d16_hi v84, v123 offset:33664
	v_and_b32_e32 v64, 0x7fffffff, v20
	v_and_b32_e32 v65, 0x7fffffff, v21
	v_cmp_gt_f32_e64 s[2:3], 0, v20
	v_cmp_gt_f32_e64 s[8:9], 0, v21
	v_pk_fma_f32 v[64:65], v[64:65], v[88:89], 1.0 op_sel_hi:[1,1,0]
	v_rcp_f32_e32 v64, v64
	v_rcp_f32_e32 v65, v65
	v_pk_mul_f32 v[68:69], v[20:21], v[20:21]
	v_pk_mul_f32 v[68:69], v[68:69], v[100:101]
	v_exp_f32_e32 v68, v68
	v_exp_f32_e32 v69, v69
	v_pk_fma_f32 v[66:67], v[64:65], v[90:91], v[92:93]
	v_pk_fma_f32 v[66:67], v[64:65], v[66:67], v[94:95]
	v_pk_fma_f32 v[66:67], v[64:65], v[66:67], v[96:97]
	v_pk_fma_f32 v[66:67], v[64:65], v[66:67], v[98:99]
	v_pk_mul_f32 v[66:67], v[64:65], v[66:67]
	v_pk_mul_f32 v[66:67], v[68:69], v[66:67]
	v_pk_mul_f32 v[70:71], v[20:21], v[66:67]
	v_pk_fma_f32 v[72:73], v[20:21], v[66:67], v[20:21] neg_lo:[1,0,0] neg_hi:[1,0,0]
	v_cndmask_b32_e64 v104, v72, v70, s[2:3]
	v_cndmask_b32_e64 v105, v73, v71, s[8:9]
	v_and_b32_e32 v64, 0x7fffffff, v22
	v_and_b32_e32 v65, 0x7fffffff, v23
	v_cmp_gt_f32_e64 s[2:3], 0, v22
	v_cmp_gt_f32_e64 s[8:9], 0, v23
	v_pk_fma_f32 v[64:65], v[64:65], v[88:89], 1.0 op_sel_hi:[1,1,0]
	v_rcp_f32_e32 v64, v64
	v_rcp_f32_e32 v65, v65
	v_pk_mul_f32 v[68:69], v[22:23], v[22:23]
	v_pk_mul_f32 v[68:69], v[68:69], v[100:101]
	v_exp_f32_e32 v68, v68
	v_exp_f32_e32 v69, v69
	v_pk_fma_f32 v[66:67], v[64:65], v[90:91], v[92:93]
	v_pk_fma_f32 v[66:67], v[64:65], v[66:67], v[94:95]
	v_pk_fma_f32 v[66:67], v[64:65], v[66:67], v[96:97]
	v_pk_fma_f32 v[66:67], v[64:65], v[66:67], v[98:99]
	v_pk_mul_f32 v[66:67], v[64:65], v[66:67]
	v_pk_mul_f32 v[66:67], v[68:69], v[66:67]
	v_pk_mul_f32 v[70:71], v[22:23], v[66:67]
	v_pk_fma_f32 v[72:73], v[22:23], v[66:67], v[22:23] neg_lo:[1,0,0] neg_hi:[1,0,0]
	v_cndmask_b32_e64 v106, v72, v70, s[2:3]
	v_cndmask_b32_e64 v107, v73, v71, s[8:9]
	v_and_b32_e32 v64, 0x7fffffff, v16
	v_and_b32_e32 v65, 0x7fffffff, v17
	v_cmp_gt_f32_e64 s[2:3], 0, v16
	v_cmp_gt_f32_e64 s[8:9], 0, v17
	v_pk_fma_f32 v[64:65], v[64:65], v[88:89], 1.0 op_sel_hi:[1,1,0]
	v_rcp_f32_e32 v64, v64
	v_rcp_f32_e32 v65, v65
	v_pk_mul_f32 v[68:69], v[16:17], v[16:17]
	v_pk_mul_f32 v[68:69], v[68:69], v[100:101]
	v_exp_f32_e32 v68, v68
	v_exp_f32_e32 v69, v69
	v_pk_fma_f32 v[66:67], v[64:65], v[90:91], v[92:93]
	v_pk_fma_f32 v[66:67], v[64:65], v[66:67], v[94:95]
	v_pk_fma_f32 v[66:67], v[64:65], v[66:67], v[96:97]
	v_pk_fma_f32 v[66:67], v[64:65], v[66:67], v[98:99]
	v_pk_mul_f32 v[66:67], v[64:65], v[66:67]
	v_pk_mul_f32 v[66:67], v[68:69], v[66:67]
	v_pk_mul_f32 v[70:71], v[16:17], v[66:67]
	v_pk_fma_f32 v[72:73], v[16:17], v[66:67], v[16:17] neg_lo:[1,0,0] neg_hi:[1,0,0]
	v_cndmask_b32_e64 v108, v72, v70, s[2:3]
	v_cndmask_b32_e64 v109, v73, v71, s[8:9]
	v_and_b32_e32 v64, 0x7fffffff, v18
	v_and_b32_e32 v65, 0x7fffffff, v19
	v_cmp_gt_f32_e64 s[2:3], 0, v18
	v_cmp_gt_f32_e64 s[8:9], 0, v19
	v_pk_fma_f32 v[64:65], v[64:65], v[88:89], 1.0 op_sel_hi:[1,1,0]
	v_rcp_f32_e32 v64, v64
	v_rcp_f32_e32 v65, v65
	v_pk_mul_f32 v[68:69], v[18:19], v[18:19]
	v_pk_mul_f32 v[68:69], v[68:69], v[100:101]
	v_exp_f32_e32 v68, v68
	v_exp_f32_e32 v69, v69
	v_pk_fma_f32 v[66:67], v[64:65], v[90:91], v[92:93]
	v_pk_fma_f32 v[66:67], v[64:65], v[66:67], v[94:95]
	v_pk_fma_f32 v[66:67], v[64:65], v[66:67], v[96:97]
	v_pk_fma_f32 v[66:67], v[64:65], v[66:67], v[98:99]
	v_pk_mul_f32 v[66:67], v[64:65], v[66:67]
	v_pk_mul_f32 v[66:67], v[68:69], v[66:67]
	v_pk_mul_f32 v[70:71], v[18:19], v[66:67]
	v_pk_fma_f32 v[72:73], v[18:19], v[66:67], v[18:19] neg_lo:[1,0,0] neg_hi:[1,0,0]
	v_cndmask_b32_e64 v110, v72, v70, s[2:3]
	v_cndmask_b32_e64 v111, v73, v71, s[8:9]
	v_pk_mul_f32 v[64:65], v[104:105], v[104:105]
	v_pk_fma_f32 v[64:65], v[106:107], v[106:107], v[64:65]
	v_pk_fma_f32 v[64:65], v[108:109], v[108:109], v[64:65]
	v_pk_fma_f32 v[64:65], v[110:111], v[110:111], v[64:65]
	v_add_f32_e32 v117, v64, v65
	v_cvt_pk_bf16_f32 v120, v104, v105
	v_cvt_pk_bf16_f32 v121, v106, v107
	v_cvt_pk_bf16_f32 v122, v108, v109
	v_cvt_pk_bf16_f32 v123, v110, v111
	ds_write_b16 v84, v120 offset:32800
	ds_write_b16_d16_hi v84, v120 offset:32928
	ds_write_b16 v84, v121 offset:33056
	ds_write_b16_d16_hi v84, v121 offset:33184
	ds_write_b16 v84, v122 offset:33312
	ds_write_b16_d16_hi v84, v122 offset:33440
	ds_write_b16 v84, v123 offset:33568
	ds_write_b16_d16_hi v84, v123 offset:33696
	v_and_b32_e32 v64, 0x7fffffff, v12
	v_and_b32_e32 v65, 0x7fffffff, v13
	v_cmp_gt_f32_e64 s[2:3], 0, v12
	v_cmp_gt_f32_e64 s[8:9], 0, v13
	v_pk_fma_f32 v[64:65], v[64:65], v[88:89], 1.0 op_sel_hi:[1,1,0]
	v_rcp_f32_e32 v64, v64
	v_rcp_f32_e32 v65, v65
	v_pk_mul_f32 v[68:69], v[12:13], v[12:13]
	v_pk_mul_f32 v[68:69], v[68:69], v[100:101]
	v_exp_f32_e32 v68, v68
	v_exp_f32_e32 v69, v69
	v_pk_fma_f32 v[66:67], v[64:65], v[90:91], v[92:93]
	v_pk_fma_f32 v[66:67], v[64:65], v[66:67], v[94:95]
	v_pk_fma_f32 v[66:67], v[64:65], v[66:67], v[96:97]
	v_pk_fma_f32 v[66:67], v[64:65], v[66:67], v[98:99]
	v_pk_mul_f32 v[66:67], v[64:65], v[66:67]
	v_pk_mul_f32 v[66:67], v[68:69], v[66:67]
	v_pk_mul_f32 v[70:71], v[12:13], v[66:67]
	v_pk_fma_f32 v[72:73], v[12:13], v[66:67], v[12:13] neg_lo:[1,0,0] neg_hi:[1,0,0]
	v_cndmask_b32_e64 v104, v72, v70, s[2:3]
	v_cndmask_b32_e64 v105, v73, v71, s[8:9]
	v_and_b32_e32 v64, 0x7fffffff, v14
	v_and_b32_e32 v65, 0x7fffffff, v15
	v_cmp_gt_f32_e64 s[2:3], 0, v14
	v_cmp_gt_f32_e64 s[8:9], 0, v15
	v_pk_fma_f32 v[64:65], v[64:65], v[88:89], 1.0 op_sel_hi:[1,1,0]
	v_rcp_f32_e32 v64, v64
	v_rcp_f32_e32 v65, v65
	v_pk_mul_f32 v[68:69], v[14:15], v[14:15]
	v_pk_mul_f32 v[68:69], v[68:69], v[100:101]
	v_exp_f32_e32 v68, v68
	v_exp_f32_e32 v69, v69
	v_pk_fma_f32 v[66:67], v[64:65], v[90:91], v[92:93]
	v_pk_fma_f32 v[66:67], v[64:65], v[66:67], v[94:95]
	v_pk_fma_f32 v[66:67], v[64:65], v[66:67], v[96:97]
	v_pk_fma_f32 v[66:67], v[64:65], v[66:67], v[98:99]
	v_pk_mul_f32 v[66:67], v[64:65], v[66:67]
	v_pk_mul_f32 v[66:67], v[68:69], v[66:67]
	v_pk_mul_f32 v[70:71], v[14:15], v[66:67]
	v_pk_fma_f32 v[72:73], v[14:15], v[66:67], v[14:15] neg_lo:[1,0,0] neg_hi:[1,0,0]
	v_cndmask_b32_e64 v106, v72, v70, s[2:3]
	v_cndmask_b32_e64 v107, v73, v71, s[8:9]
	v_and_b32_e32 v64, 0x7fffffff, v8
	v_and_b32_e32 v65, 0x7fffffff, v9
	v_cmp_gt_f32_e64 s[2:3], 0, v8
	v_cmp_gt_f32_e64 s[8:9], 0, v9
	v_pk_fma_f32 v[64:65], v[64:65], v[88:89], 1.0 op_sel_hi:[1,1,0]
	v_rcp_f32_e32 v64, v64
	v_rcp_f32_e32 v65, v65
	v_pk_mul_f32 v[68:69], v[8:9], v[8:9]
	v_pk_mul_f32 v[68:69], v[68:69], v[100:101]
	v_exp_f32_e32 v68, v68
	v_exp_f32_e32 v69, v69
	v_pk_fma_f32 v[66:67], v[64:65], v[90:91], v[92:93]
	v_pk_fma_f32 v[66:67], v[64:65], v[66:67], v[94:95]
	v_pk_fma_f32 v[66:67], v[64:65], v[66:67], v[96:97]
	v_pk_fma_f32 v[66:67], v[64:65], v[66:67], v[98:99]
	v_pk_mul_f32 v[66:67], v[64:65], v[66:67]
	v_pk_mul_f32 v[66:67], v[68:69], v[66:67]
	v_pk_mul_f32 v[70:71], v[8:9], v[66:67]
	v_pk_fma_f32 v[72:73], v[8:9], v[66:67], v[8:9] neg_lo:[1,0,0] neg_hi:[1,0,0]
	v_cndmask_b32_e64 v108, v72, v70, s[2:3]
	v_cndmask_b32_e64 v109, v73, v71, s[8:9]
	v_and_b32_e32 v64, 0x7fffffff, v10
	v_and_b32_e32 v65, 0x7fffffff, v11
	v_cmp_gt_f32_e64 s[2:3], 0, v10
	v_cmp_gt_f32_e64 s[8:9], 0, v11
	v_pk_fma_f32 v[64:65], v[64:65], v[88:89], 1.0 op_sel_hi:[1,1,0]
	v_rcp_f32_e32 v64, v64
	v_rcp_f32_e32 v65, v65
	v_pk_mul_f32 v[68:69], v[10:11], v[10:11]
	v_pk_mul_f32 v[68:69], v[68:69], v[100:101]
	v_exp_f32_e32 v68, v68
	v_exp_f32_e32 v69, v69
	v_pk_fma_f32 v[66:67], v[64:65], v[90:91], v[92:93]
	v_pk_fma_f32 v[66:67], v[64:65], v[66:67], v[94:95]
	v_pk_fma_f32 v[66:67], v[64:65], v[66:67], v[96:97]
	v_pk_fma_f32 v[66:67], v[64:65], v[66:67], v[98:99]
	v_pk_mul_f32 v[66:67], v[64:65], v[66:67]
	v_pk_mul_f32 v[66:67], v[68:69], v[66:67]
	v_pk_mul_f32 v[70:71], v[10:11], v[66:67]
	v_pk_fma_f32 v[72:73], v[10:11], v[66:67], v[10:11] neg_lo:[1,0,0] neg_hi:[1,0,0]
	v_cndmask_b32_e64 v110, v72, v70, s[2:3]
	v_cndmask_b32_e64 v111, v73, v71, s[8:9]
	v_pk_mul_f32 v[64:65], v[104:105], v[104:105]
	v_pk_fma_f32 v[64:65], v[106:107], v[106:107], v[64:65]
	v_pk_fma_f32 v[64:65], v[108:109], v[108:109], v[64:65]
	v_pk_fma_f32 v[64:65], v[110:111], v[110:111], v[64:65]
	v_add_f32_e32 v118, v64, v65
	v_cvt_pk_bf16_f32 v120, v104, v105
	v_cvt_pk_bf16_f32 v121, v106, v107
	v_cvt_pk_bf16_f32 v122, v108, v109
	v_cvt_pk_bf16_f32 v123, v110, v111
	ds_write_b16 v84, v120 offset:32832
	ds_write_b16_d16_hi v84, v120 offset:32960
	ds_write_b16 v84, v121 offset:33088
	ds_write_b16_d16_hi v84, v121 offset:33216
	ds_write_b16 v84, v122 offset:33344
	ds_write_b16_d16_hi v84, v122 offset:33472
	ds_write_b16 v84, v123 offset:33600
	ds_write_b16_d16_hi v84, v123 offset:33728
	v_and_b32_e32 v64, 0x7fffffff, v4
	v_and_b32_e32 v65, 0x7fffffff, v5
	v_cmp_gt_f32_e64 s[2:3], 0, v4
	v_cmp_gt_f32_e64 s[8:9], 0, v5
	v_pk_fma_f32 v[64:65], v[64:65], v[88:89], 1.0 op_sel_hi:[1,1,0]
	v_rcp_f32_e32 v64, v64
	v_rcp_f32_e32 v65, v65
	v_pk_mul_f32 v[68:69], v[4:5], v[4:5]
	v_pk_mul_f32 v[68:69], v[68:69], v[100:101]
	v_exp_f32_e32 v68, v68
	v_exp_f32_e32 v69, v69
	v_pk_fma_f32 v[66:67], v[64:65], v[90:91], v[92:93]
	v_pk_fma_f32 v[66:67], v[64:65], v[66:67], v[94:95]
	v_pk_fma_f32 v[66:67], v[64:65], v[66:67], v[96:97]
	v_pk_fma_f32 v[66:67], v[64:65], v[66:67], v[98:99]
	v_pk_mul_f32 v[66:67], v[64:65], v[66:67]
	v_pk_mul_f32 v[66:67], v[68:69], v[66:67]
	v_pk_mul_f32 v[70:71], v[4:5], v[66:67]
	v_pk_fma_f32 v[72:73], v[4:5], v[66:67], v[4:5] neg_lo:[1,0,0] neg_hi:[1,0,0]
	v_cndmask_b32_e64 v104, v72, v70, s[2:3]
	v_cndmask_b32_e64 v105, v73, v71, s[8:9]
	v_and_b32_e32 v64, 0x7fffffff, v6
	v_and_b32_e32 v65, 0x7fffffff, v7
	v_cmp_gt_f32_e64 s[2:3], 0, v6
	v_cmp_gt_f32_e64 s[8:9], 0, v7
	v_pk_fma_f32 v[64:65], v[64:65], v[88:89], 1.0 op_sel_hi:[1,1,0]
	v_rcp_f32_e32 v64, v64
	v_rcp_f32_e32 v65, v65
	v_pk_mul_f32 v[68:69], v[6:7], v[6:7]
	v_pk_mul_f32 v[68:69], v[68:69], v[100:101]
	v_exp_f32_e32 v68, v68
	v_exp_f32_e32 v69, v69
	v_pk_fma_f32 v[66:67], v[64:65], v[90:91], v[92:93]
	v_pk_fma_f32 v[66:67], v[64:65], v[66:67], v[94:95]
	v_pk_fma_f32 v[66:67], v[64:65], v[66:67], v[96:97]
	v_pk_fma_f32 v[66:67], v[64:65], v[66:67], v[98:99]
	v_pk_mul_f32 v[66:67], v[64:65], v[66:67]
	v_pk_mul_f32 v[66:67], v[68:69], v[66:67]
	v_pk_mul_f32 v[70:71], v[6:7], v[66:67]
	v_pk_fma_f32 v[72:73], v[6:7], v[66:67], v[6:7] neg_lo:[1,0,0] neg_hi:[1,0,0]
	v_cndmask_b32_e64 v106, v72, v70, s[2:3]
	v_cndmask_b32_e64 v107, v73, v71, s[8:9]
	v_and_b32_e32 v64, 0x7fffffff, v0
	v_and_b32_e32 v65, 0x7fffffff, v1
	v_cmp_gt_f32_e64 s[2:3], 0, v0
	v_cmp_gt_f32_e64 s[8:9], 0, v1
	v_pk_fma_f32 v[64:65], v[64:65], v[88:89], 1.0 op_sel_hi:[1,1,0]
	v_rcp_f32_e32 v64, v64
	v_rcp_f32_e32 v65, v65
	v_pk_mul_f32 v[68:69], v[0:1], v[0:1]
	v_pk_mul_f32 v[68:69], v[68:69], v[100:101]
	v_exp_f32_e32 v68, v68
	v_exp_f32_e32 v69, v69
	v_pk_fma_f32 v[66:67], v[64:65], v[90:91], v[92:93]
	v_pk_fma_f32 v[66:67], v[64:65], v[66:67], v[94:95]
	v_pk_fma_f32 v[66:67], v[64:65], v[66:67], v[96:97]
	v_pk_fma_f32 v[66:67], v[64:65], v[66:67], v[98:99]
	v_pk_mul_f32 v[66:67], v[64:65], v[66:67]
	v_pk_mul_f32 v[66:67], v[68:69], v[66:67]
	v_pk_mul_f32 v[70:71], v[0:1], v[66:67]
	v_pk_fma_f32 v[72:73], v[0:1], v[66:67], v[0:1] neg_lo:[1,0,0] neg_hi:[1,0,0]
	v_cndmask_b32_e64 v108, v72, v70, s[2:3]
	v_cndmask_b32_e64 v109, v73, v71, s[8:9]
	v_and_b32_e32 v64, 0x7fffffff, v2
	v_and_b32_e32 v65, 0x7fffffff, v3
	v_cmp_gt_f32_e64 s[2:3], 0, v2
	v_cmp_gt_f32_e64 s[8:9], 0, v3
	v_pk_fma_f32 v[64:65], v[64:65], v[88:89], 1.0 op_sel_hi:[1,1,0]
	v_rcp_f32_e32 v64, v64
	v_rcp_f32_e32 v65, v65
	v_pk_mul_f32 v[68:69], v[2:3], v[2:3]
	v_pk_mul_f32 v[68:69], v[68:69], v[100:101]
	v_exp_f32_e32 v68, v68
	v_exp_f32_e32 v69, v69
	v_pk_fma_f32 v[66:67], v[64:65], v[90:91], v[92:93]
	v_pk_fma_f32 v[66:67], v[64:65], v[66:67], v[94:95]
	v_pk_fma_f32 v[66:67], v[64:65], v[66:67], v[96:97]
	v_pk_fma_f32 v[66:67], v[64:65], v[66:67], v[98:99]
	v_pk_mul_f32 v[66:67], v[64:65], v[66:67]
	v_pk_mul_f32 v[66:67], v[68:69], v[66:67]
	v_pk_mul_f32 v[70:71], v[2:3], v[66:67]
	v_pk_fma_f32 v[72:73], v[2:3], v[66:67], v[2:3] neg_lo:[1,0,0] neg_hi:[1,0,0]
	v_cndmask_b32_e64 v110, v72, v70, s[2:3]
	v_cndmask_b32_e64 v111, v73, v71, s[8:9]
	v_pk_mul_f32 v[64:65], v[104:105], v[104:105]
	v_pk_fma_f32 v[64:65], v[106:107], v[106:107], v[64:65]
	v_pk_fma_f32 v[64:65], v[108:109], v[108:109], v[64:65]
	v_pk_fma_f32 v[64:65], v[110:111], v[110:111], v[64:65]
	v_add_f32_e32 v119, v64, v65
	v_cvt_pk_bf16_f32 v120, v104, v105
	v_cvt_pk_bf16_f32 v121, v106, v107
	v_cvt_pk_bf16_f32 v122, v108, v109
	v_cvt_pk_bf16_f32 v123, v110, v111
	ds_write_b16 v84, v120 offset:32864
	ds_write_b16_d16_hi v84, v120 offset:32992
	ds_write_b16 v84, v121 offset:33120
	ds_write_b16_d16_hi v84, v121 offset:33248
	ds_write_b16 v84, v122 offset:33376
	ds_write_b16_d16_hi v84, v122 offset:33504
	ds_write_b16 v84, v123 offset:33632
	ds_write_b16_d16_hi v84, v123 offset:33760
	ds_bpermute_b32 v64, v85, v112
	ds_bpermute_b32 v65, v85, v113
	ds_bpermute_b32 v66, v85, v114
	ds_bpermute_b32 v67, v85, v115
	ds_bpermute_b32 v68, v85, v116
	ds_bpermute_b32 v69, v85, v117
	ds_bpermute_b32 v70, v85, v118
	ds_bpermute_b32 v71, v85, v119
	s_waitcnt lgkmcnt(0)
	v_add_f32_e32 v112, v112, v64
	v_add_f32_e32 v113, v113, v65
	v_add_f32_e32 v114, v114, v66
	v_add_f32_e32 v115, v115, v67
	v_add_f32_e32 v116, v116, v68
	v_add_f32_e32 v117, v117, v69
	v_add_f32_e32 v118, v118, v70
	v_add_f32_e32 v119, v119, v71
	ds_bpermute_b32 v64, v86, v112
	ds_bpermute_b32 v65, v86, v113
	ds_bpermute_b32 v66, v86, v114
	ds_bpermute_b32 v67, v86, v115
	ds_bpermute_b32 v68, v86, v116
	ds_bpermute_b32 v69, v86, v117
	ds_bpermute_b32 v70, v86, v118
	ds_bpermute_b32 v71, v86, v119
	s_waitcnt lgkmcnt(0)
	v_add_f32_e32 v112, v112, v64
	v_add_f32_e32 v113, v113, v65
	v_add_f32_e32 v114, v114, v66
	v_add_f32_e32 v115, v115, v67
	v_add_f32_e32 v116, v116, v68
	v_add_f32_e32 v117, v117, v69
	v_add_f32_e32 v118, v118, v70
	v_add_f32_e32 v119, v119, v71
	v_lshrrev_b32_e32 v86, 6, v215
	v_and_b32_e32 v87, 3, v86
	v_lshrrev_b32_e32 v121, 2, v86
	v_and_b32_e32 v124, 15, v214
	v_lshl_add_u32 v124, v121, 6, v124
	s_lshl_b32 s2, s10, 8
	v_add_u32_e32 v124, s2, v124
	v_mul_u32_u24_e32 v124, 0x90, v124
	s_lshl_b32 s2, s54, 4
	s_add_i32 s2, s2, 48
	v_lshl_add_u32 v124, v87, 2, v124
	v_add_u32_e32 v124, s2, v124
	v_cmp_gt_u32_e64 s[2:3], 16, v214
	s_and_saveexec_b64 s[8:9], s[2:3]
	global_store_dword v124, v112, s[82:83]
	v_add_u32_e32 v125, 0x900, v124
	global_store_dword v125, v113, s[82:83]
	v_add_u32_e32 v125, 0x1200, v124
	global_store_dword v125, v114, s[82:83]
	v_add_u32_e32 v125, 0x1b00, v124
	global_store_dword v125, v115, s[82:83]
	v_add_u32_e32 v125, 0x4800, v124
	global_store_dword v125, v116, s[82:83]
	v_add_u32_e32 v125, 0x5100, v124
	global_store_dword v125, v117, s[82:83]
	v_add_u32_e32 v125, 0x5a00, v124
	global_store_dword v125, v118, s[82:83]
	v_add_u32_e32 v125, 0x6300, v124
	global_store_dword v125, v119, s[82:83]
	s_or_b64 exec, exec, s[8:9]
	v_lshlrev_b32_e32 v85, 4, v214
	v_lshl_add_u32 v85, v86, 10, v85
	ds_read_b128 v[88:91], v85
	ds_read_b128 v[92:95], v85 offset:8192
	ds_read_b128 v[96:99], v85 offset:16384
	ds_read_b128 v[100:103], v85 offset:24576
	ds_read_b128 v[104:107], v85 offset:32768
	ds_read_b128 v[108:111], v85 offset:40960
	ds_read_b128 v[112:115], v85 offset:49152
	ds_read_b128 v[116:119], v85 offset:57344
	s_add_u32 s34, s74, 0x4b00000
	s_addc_u32 s35, s75, 0
	s_sub_i32 s2, s54, 2
	s_lshl_b32 s2, s2, 7
	v_lshrrev_b32_e32 v122, 3, v214
	v_lshl_add_u32 v87, v87, 5, v122
	v_add_u32_e32 v87, s2, v87
	v_lshlrev_b32_e32 v87, 13, v87
	v_and_b32_e32 v122, 7, v214
	v_lshlrev_b32_e32 v122, 3, v122
	v_lshl_add_u32 v122, v121, 6, v122
	s_lshl_b32 s2, s10, 8
	v_add3_u32 v87, v87, v122, s2
	v_lshlrev_b32_e32 v87, 1, v87
	s_waitcnt lgkmcnt(7)
	global_store_dwordx4 v87, v[88:91], s[34:35]
	v_add_u32_e32 v120, 0x20000, v87
	s_waitcnt lgkmcnt(6)
	global_store_dwordx4 v120, v[92:95], s[34:35]
	v_add_u32_e32 v120, 0x40000, v87
	s_waitcnt lgkmcnt(5)
	global_store_dwordx4 v120, v[96:99], s[34:35]
	v_add_u32_e32 v120, 0x60000, v87
	s_waitcnt lgkmcnt(4)
	global_store_dwordx4 v120, v[100:103], s[34:35]
	v_add_u32_e32 v120, 0x100, v87
	s_waitcnt lgkmcnt(3)
	global_store_dwordx4 v120, v[104:107], s[34:35]
	v_add_u32_e32 v120, 0x20100, v87
	s_waitcnt lgkmcnt(2)
	global_store_dwordx4 v120, v[108:111], s[34:35]
	v_add_u32_e32 v120, 0x40100, v87
	s_waitcnt lgkmcnt(1)
	global_store_dwordx4 v120, v[112:115], s[34:35]
	v_add_u32_e32 v120, 0x60100, v87
	s_waitcnt lgkmcnt(0)
	global_store_dwordx4 v120, v[116:119], s[34:35]
